# baseline (speedup 1.0000x reference)
.LBB0_568:
	s_lshl_b64 s[40:41], s[6:7], 2
	s_add_u32 s40, s4, s40
	s_addc_u32 s41, s5, s41
	v_cndmask_b32_e64 v76, 0, 1, s[46:47]
	v_lshl_add_u32 v128, s6, 2, v99
	v_mov_b64_e32 v[126:127], s[40:41]
	v_cmp_ne_u32_e32 vcc, 1, v76
	v_cndmask_b32_e64 v76, v74, v75, s[46:47]
	ds_read_b128 v[80:83], v128
	ds_read_b128 v[88:91], v128 offset:16
	ds_read_b128 v[102:105], v128 offset:32
	ds_read_b128 v[110:113], v128 offset:48
	ds_read_b128 v[84:87], v128 offset:64
	flat_load_dwordx4 v[106:109], v[126:127]
	flat_load_dwordx4 v[114:117], v[126:127] offset:64
	v_lshlrev_b32_e32 v76, 7, v76
	v_mov_b32_e32 v77, v0
	v_lshl_add_u64 v[130:131], s[18:19], 0, v[76:77]
	flat_load_dwordx4 v[118:121], v[130:131]
	s_waitcnt lgkmcnt(0)
	v_mov_b32_e32 v76, v80
	v_mov_b32_e32 v77, v84
	v_mov_b32_e32 v84, v81
	s_and_b64 vcc, exec, vcc
	s_mov_b64 s[46:47], 0
	s_waitcnt vmcnt(0)
	v_mov_b32_e32 v78, v106
	v_mov_b32_e32 v79, v114
	v_pk_mul_f32 v[76:77], v[76:77], v[78:79]
	v_mov_b32_e32 v114, v107
	v_pk_mul_f32 v[78:79], v[72:73], v[76:77]
	s_nop 0
	v_pk_mul_f32 v[76:77], v[78:79], v[118:119]
	v_pk_mul_f32 v[78:79], v[78:79], v[118:119] op_sel:[1,0] op_sel_hi:[0,1]
	v_sub_f32_e32 v77, v76, v77
	v_add_f32_e32 v76, v78, v79
	v_pk_mul_f32 v[78:79], v[84:85], v[114:115]
	v_mov_b32_e32 v84, v108
	v_pk_mul_f32 v[80:81], v[72:73], v[78:79]
	v_mov_b32_e32 v85, v116
	v_pk_mul_f32 v[78:79], v[80:81], v[120:121]
	v_pk_mul_f32 v[80:81], v[80:81], v[120:121] op_sel:[1,0] op_sel_hi:[0,1]
	flat_load_dwordx4 v[118:121], v[130:131] offset:16
	v_sub_f32_e32 v79, v78, v79
	v_add_f32_e32 v78, v80, v81
	v_mov_b32_e32 v80, v82
	v_mov_b32_e32 v81, v86
	v_pk_mul_f32 v[80:81], v[80:81], v[84:85]
	v_mov_b32_e32 v86, v83
	v_pk_mul_f32 v[84:85], v[72:73], v[80:81]
	v_mov_b32_e32 v116, v109
	v_pk_mul_f32 v[82:83], v[86:87], v[116:117]
	ds_read_b128 v[106:109], v128 offset:80
	v_cvt_pk_bf16_f32 v76, v76, v78
	s_waitcnt vmcnt(0) lgkmcnt(0)
	v_pk_mul_f32 v[80:81], v[84:85], v[118:119]
	v_pk_mul_f32 v[84:85], v[84:85], v[118:119] op_sel:[1,0] op_sel_hi:[0,1]
	v_sub_f32_e32 v81, v80, v81
	v_add_f32_e32 v80, v84, v85
	v_pk_mul_f32 v[84:85], v[72:73], v[82:83]
	s_nop 0
	v_pk_mul_f32 v[82:83], v[84:85], v[120:121]
	v_pk_mul_f32 v[84:85], v[84:85], v[120:121] op_sel:[1,0] op_sel_hi:[0,1]
	flat_load_dwordx4 v[114:117], v[126:127] offset:16
	flat_load_dwordx4 v[118:121], v[126:127] offset:80
	flat_load_dwordx4 v[122:125], v[130:131] offset:32
	v_sub_f32_e32 v83, v82, v83
	v_add_f32_e32 v82, v84, v85
	v_mov_b32_e32 v84, v88
	v_mov_b32_e32 v85, v106
	v_mov_b32_e32 v106, v89
	s_waitcnt vmcnt(0) lgkmcnt(0)
	v_mov_b32_e32 v86, v114
	v_mov_b32_e32 v87, v118
	v_pk_mul_f32 v[84:85], v[84:85], v[86:87]
	v_mov_b32_e32 v118, v115
	v_pk_mul_f32 v[86:87], v[72:73], v[84:85]
	v_mov_b32_e32 v92, v116
	v_pk_mul_f32 v[84:85], v[86:87], v[122:123]
	v_pk_mul_f32 v[86:87], v[86:87], v[122:123] op_sel:[1,0] op_sel_hi:[0,1]
	v_sub_f32_e32 v85, v84, v85
	v_add_f32_e32 v84, v86, v87
	v_pk_mul_f32 v[86:87], v[106:107], v[118:119]
	v_mov_b32_e32 v93, v120
	v_pk_mul_f32 v[88:89], v[72:73], v[86:87]
	v_mov_b32_e32 v120, v117
	v_pk_mul_f32 v[86:87], v[88:89], v[124:125]
	v_pk_mul_f32 v[88:89], v[88:89], v[124:125] op_sel:[1,0] op_sel_hi:[0,1]
	flat_load_dwordx4 v[122:125], v[130:131] offset:48
	v_sub_f32_e32 v87, v86, v87
	v_add_f32_e32 v86, v88, v89
	v_mov_b32_e32 v88, v90
	v_mov_b32_e32 v89, v108
	v_pk_mul_f32 v[88:89], v[88:89], v[92:93]
	v_mov_b32_e32 v108, v91
	v_pk_mul_f32 v[92:93], v[72:73], v[88:89]
	v_pk_mul_f32 v[90:91], v[108:109], v[120:121]
	ds_read_b128 v[106:109], v128 offset:96
	flat_load_dwordx4 v[114:117], v[126:127] offset:32
	flat_load_dwordx4 v[118:121], v[126:127] offset:96
	v_cvt_pk_bf16_f32 v78, v84, v86
	s_waitcnt vmcnt(0) lgkmcnt(0)
	v_pk_mul_f32 v[88:89], v[92:93], v[122:123]
	v_pk_mul_f32 v[92:93], v[92:93], v[122:123] op_sel:[1,0] op_sel_hi:[0,1]
	v_sub_f32_e32 v89, v88, v89
	v_add_f32_e32 v88, v92, v93
	v_pk_mul_f32 v[92:93], v[72:73], v[90:91]
	v_mov_b32_e32 v100, v114
	v_pk_mul_f32 v[90:91], v[92:93], v[124:125]
	v_pk_mul_f32 v[92:93], v[92:93], v[124:125] op_sel:[1,0] op_sel_hi:[0,1]
	flat_load_dwordx4 v[122:125], v[130:131] offset:64
	v_sub_f32_e32 v91, v90, v91
	v_add_f32_e32 v90, v92, v93
	v_mov_b32_e32 v92, v102
	v_mov_b32_e32 v93, v106
	v_mov_b32_e32 v101, v118
	v_pk_mul_f32 v[92:93], v[92:93], v[100:101]
	v_mov_b32_e32 v106, v103
	v_pk_mul_f32 v[100:101], v[72:73], v[92:93]
	v_mov_b32_e32 v118, v115
	s_waitcnt vmcnt(0) lgkmcnt(0)
	v_pk_mul_f32 v[92:93], v[100:101], v[122:123]
	v_pk_mul_f32 v[100:101], v[100:101], v[122:123] op_sel:[1,0] op_sel_hi:[0,1]
	v_sub_f32_e32 v93, v92, v93
	v_add_f32_e32 v92, v100, v101
	v_pk_mul_f32 v[100:101], v[106:107], v[118:119]
	v_mov_b32_e32 v106, v116
	v_pk_mul_f32 v[102:103], v[72:73], v[100:101]
	v_mov_b32_e32 v107, v120
	v_pk_mul_f32 v[100:101], v[102:103], v[124:125]
	v_pk_mul_f32 v[102:103], v[102:103], v[124:125] op_sel:[1,0] op_sel_hi:[0,1]
	flat_load_dwordx4 v[122:125], v[130:131] offset:80
	v_sub_f32_e32 v101, v100, v101
	v_add_f32_e32 v100, v102, v103
	v_mov_b32_e32 v102, v104
	v_mov_b32_e32 v103, v108
	v_pk_mul_f32 v[102:103], v[102:103], v[106:107]
	v_mov_b32_e32 v108, v105
	v_pk_mul_f32 v[106:107], v[72:73], v[102:103]
	v_mov_b32_e32 v120, v117
	v_pk_mul_f32 v[104:105], v[108:109], v[120:121]
	ds_read_b128 v[114:117], v128 offset:112
	s_waitcnt vmcnt(0) lgkmcnt(0)
	v_pk_mul_f32 v[102:103], v[106:107], v[122:123]
	v_pk_mul_f32 v[106:107], v[106:107], v[122:123] op_sel:[1,0] op_sel_hi:[0,1]
	v_sub_f32_e32 v103, v102, v103
	v_add_f32_e32 v102, v106, v107
	v_pk_mul_f32 v[106:107], v[72:73], v[104:105]
	s_nop 0
	v_pk_mul_f32 v[104:105], v[106:107], v[124:125]
	v_pk_mul_f32 v[106:107], v[106:107], v[124:125] op_sel:[1,0] op_sel_hi:[0,1]
	flat_load_dwordx4 v[118:121], v[126:127] offset:48
	flat_load_dwordx4 v[122:125], v[126:127] offset:112
	v_sub_f32_e32 v105, v104, v105
	flat_load_dwordx4 v[126:129], v[130:131] offset:96
	v_add_f32_e32 v104, v106, v107
	v_mov_b32_e32 v106, v110
	v_mov_b32_e32 v107, v114
	v_mov_b32_e32 v114, v111
	s_waitcnt vmcnt(0) lgkmcnt(0)
	v_mov_b32_e32 v108, v118
	v_mov_b32_e32 v109, v122
	v_pk_mul_f32 v[106:107], v[106:107], v[108:109]
	v_mov_b32_e32 v122, v119
	v_pk_mul_f32 v[108:109], v[72:73], v[106:107]
	v_lshl_add_u64 v[118:119], s[6:7], 1, v[70:71]
	v_lshl_add_u32 v251, s6, 1, v99
	v_pk_mul_f32 v[106:107], v[108:109], v[126:127]
	v_pk_mul_f32 v[108:109], v[108:109], v[126:127] op_sel:[1,0] op_sel_hi:[0,1]
	v_sub_f32_e32 v107, v106, v107
	v_add_f32_e32 v106, v108, v109
	v_pk_mul_f32 v[108:109], v[114:115], v[122:123]
	v_mov_b32_e32 v114, v120
	v_pk_mul_f32 v[110:111], v[72:73], v[108:109]
	v_mov_b32_e32 v115, v124
	v_pk_mul_f32 v[108:109], v[110:111], v[128:129]
	v_pk_mul_f32 v[110:111], v[110:111], v[128:129] op_sel:[1,0] op_sel_hi:[0,1]
	flat_load_dwordx4 v[126:129], v[130:131] offset:112
	v_sub_f32_e32 v109, v108, v109
	v_add_f32_e32 v108, v110, v111
	v_mov_b32_e32 v110, v112
	v_mov_b32_e32 v111, v116
	v_pk_mul_f32 v[110:111], v[110:111], v[114:115]
	v_mov_b32_e32 v116, v113
	v_pk_mul_f32 v[114:115], v[72:73], v[110:111]
	v_mov_b32_e32 v124, v121
	v_pk_mul_f32 v[112:113], v[116:117], v[124:125]
	v_cvt_pk_bf16_f32 v116, v85, v87
	v_cvt_pk_bf16_f32 v117, v89, v91
	s_mov_b64 s[6:7], 32
	s_waitcnt vmcnt(0) lgkmcnt(0)
	v_pk_mul_f32 v[110:111], v[114:115], v[126:127]
	v_pk_mul_f32 v[114:115], v[114:115], v[126:127] op_sel:[1,0] op_sel_hi:[0,1]
	v_sub_f32_e32 v111, v110, v111
	v_add_f32_e32 v110, v114, v115
	v_pk_mul_f32 v[114:115], v[72:73], v[112:113]
	s_nop 0
	v_pk_mul_f32 v[112:113], v[114:115], v[128:129]
	v_pk_mul_f32 v[114:115], v[114:115], v[128:129] op_sel:[1,0] op_sel_hi:[0,1]
	v_sub_f32_e32 v113, v112, v113
	v_add_f32_e32 v112, v114, v115
	v_cvt_pk_bf16_f32 v114, v77, v79
	v_cvt_pk_bf16_f32 v115, v81, v83
	v_cvt_pk_bf16_f32 v77, v80, v82
	v_cvt_pk_bf16_f32 v79, v88, v90
	ds_write_b128 v251, v[114:117]
	ds_write_b128 v251, v[76:79] offset:32
	s_nop 0
	v_cvt_pk_bf16_f32 v114, v93, v101
	v_cvt_pk_bf16_f32 v115, v103, v105
	v_cvt_pk_bf16_f32 v116, v107, v109
	v_cvt_pk_bf16_f32 v117, v111, v113
	ds_write_b128 v251, v[114:117] offset:16
	v_cvt_pk_bf16_f32 v76, v92, v100
	v_cvt_pk_bf16_f32 v77, v102, v104
	v_cvt_pk_bf16_f32 v78, v106, v108
	v_cvt_pk_bf16_f32 v79, v110, v112
	ds_write_b128 v251, v[76:79] offset:48
	s_cbranch_vccz .LBB0_568
	v_and_b32_e32 v82, 63, v170
	v_lshrrev_b32_e32 v83, 3, v82
	v_sub_u32_e32 v83, v83, v82
	v_and_b32_e32 v82, 7, v82
	v_lshlrev_b32_e32 v82, 4, v82
	v_mul_i32_i24_e32 v76, 0x1400, v83
	v_add_u32_e32 v76, v76, v82
	v_mul_i32_i24_e32 v83, 0x110, v83
	v_add3_u32 v83, v83, v82, v99
	s_waitcnt lgkmcnt(0)
	ds_read_b128 v[72:75], v83 offset:0
	v_mov_b32_e32 v78, v76
	v_ashrrev_i32_e32 v79, 31, v78
	v_lshl_add_u64 v[80:81], v[78:79], 0, v[70:71]
	s_waitcnt lgkmcnt(0)
	global_store_dwordx4 v[80:81], v[72:75], off
	s_nop 1
	ds_read_b128 v[72:75], v83 offset:2176
	v_add_u32_e32 v78, 0xa000, v76
	v_ashrrev_i32_e32 v79, 31, v78
	v_lshl_add_u64 v[80:81], v[78:79], 0, v[70:71]
	s_waitcnt lgkmcnt(0)
	global_store_dwordx4 v[80:81], v[72:75], off
	s_nop 1
	ds_read_b128 v[72:75], v83 offset:4352
	v_add_u32_e32 v78, 0x14000, v76
	v_ashrrev_i32_e32 v79, 31, v78
	v_lshl_add_u64 v[80:81], v[78:79], 0, v[70:71]
	s_waitcnt lgkmcnt(0)
	global_store_dwordx4 v[80:81], v[72:75], off
	s_nop 1
	ds_read_b128 v[72:75], v83 offset:6528
	v_add_u32_e32 v78, 0x1e000, v76
	v_ashrrev_i32_e32 v79, 31, v78
	v_lshl_add_u64 v[80:81], v[78:79], 0, v[70:71]
	s_waitcnt lgkmcnt(0)
	global_store_dwordx4 v[80:81], v[72:75], off
	s_nop 1
	ds_read_b128 v[72:75], v83 offset:8704
	v_add_u32_e32 v78, 0x28000, v76
	v_ashrrev_i32_e32 v79, 31, v78
	v_lshl_add_u64 v[80:81], v[78:79], 0, v[70:71]
	s_waitcnt lgkmcnt(0)
	global_store_dwordx4 v[80:81], v[72:75], off
	s_nop 1
	ds_read_b128 v[72:75], v83 offset:10880
	v_add_u32_e32 v78, 0x32000, v76
	v_ashrrev_i32_e32 v79, 31, v78
	v_lshl_add_u64 v[80:81], v[78:79], 0, v[70:71]
	s_waitcnt lgkmcnt(0)
	global_store_dwordx4 v[80:81], v[72:75], off
	s_nop 1
	ds_read_b128 v[72:75], v83 offset:13056
	v_add_u32_e32 v78, 0x3c000, v76
	v_ashrrev_i32_e32 v79, 31, v78
	v_lshl_add_u64 v[80:81], v[78:79], 0, v[70:71]
	s_waitcnt lgkmcnt(0)
	global_store_dwordx4 v[80:81], v[72:75], off
	s_nop 1
	ds_read_b128 v[72:75], v83 offset:15232
	v_add_u32_e32 v78, 0x46000, v76
	v_ashrrev_i32_e32 v79, 31, v78
	v_lshl_add_u64 v[80:81], v[78:79], 0, v[70:71]
	s_waitcnt lgkmcnt(0)
	global_store_dwordx4 v[80:81], v[72:75], off
	s_nop 1

.LBB0_581:
	s_lshl_b64 s[40:41], s[6:7], 2
	s_add_u32 s40, s4, s40
	s_addc_u32 s41, s5, s41
	v_cndmask_b32_e64 v8, 0, 1, s[30:31]
	v_lshl_add_u32 v54, s6, 2, v1
	v_mov_b64_e32 v[52:53], s[40:41]
	v_cmp_ne_u32_e32 vcc, 1, v8
	v_cndmask_b32_e64 v8, v6, v7, s[30:31]
	ds_read_b128 v[12:15], v54
	ds_read_b128 v[20:23], v54 offset:16
	ds_read_b128 v[28:31], v54 offset:32
	ds_read_b128 v[36:39], v54 offset:48
	ds_read_b128 v[16:19], v54 offset:64
	flat_load_dwordx4 v[24:27], v[52:53]
	flat_load_dwordx4 v[32:35], v[52:53] offset:64
	v_lshlrev_b32_e32 v8, 7, v8
	v_mov_b32_e32 v9, v0
	v_lshl_add_u64 v[56:57], s[18:19], 0, v[8:9]
	flat_load_dwordx4 v[40:43], v[56:57]
	s_waitcnt lgkmcnt(0)
	v_mov_b32_e32 v8, v12
	v_mov_b32_e32 v9, v16
	v_mov_b32_e32 v16, v13
	s_and_b64 vcc, exec, vcc
	s_mov_b64 s[30:31], 0
	s_waitcnt vmcnt(0)
	v_mov_b32_e32 v10, v24
	v_mov_b32_e32 v11, v32
	v_pk_mul_f32 v[8:9], v[8:9], v[10:11]
	v_mov_b32_e32 v32, v25
	v_pk_mul_f32 v[10:11], v[4:5], v[8:9]
	s_nop 0
	v_pk_mul_f32 v[8:9], v[10:11], v[40:41]
	v_pk_mul_f32 v[10:11], v[10:11], v[40:41] op_sel:[1,0] op_sel_hi:[0,1]
	v_sub_f32_e32 v9, v8, v9
	v_add_f32_e32 v8, v10, v11
	v_pk_mul_f32 v[10:11], v[16:17], v[32:33]
	v_mov_b32_e32 v16, v26
	v_pk_mul_f32 v[12:13], v[4:5], v[10:11]
	v_mov_b32_e32 v17, v34
	v_pk_mul_f32 v[10:11], v[12:13], v[42:43]
	v_pk_mul_f32 v[12:13], v[12:13], v[42:43] op_sel:[1,0] op_sel_hi:[0,1]
	flat_load_dwordx4 v[40:43], v[56:57] offset:16
	v_sub_f32_e32 v11, v10, v11
	v_add_f32_e32 v10, v12, v13
	v_mov_b32_e32 v12, v14
	v_mov_b32_e32 v13, v18
	v_pk_mul_f32 v[12:13], v[12:13], v[16:17]
	v_mov_b32_e32 v18, v15
	v_pk_mul_f32 v[16:17], v[4:5], v[12:13]
	v_mov_b32_e32 v34, v27
	v_pk_mul_f32 v[14:15], v[18:19], v[34:35]
	ds_read_b128 v[24:27], v54 offset:80
	v_cvt_pk_bf16_f32 v8, v8, v10
	s_waitcnt vmcnt(0) lgkmcnt(0)
	v_pk_mul_f32 v[12:13], v[16:17], v[40:41]
	v_pk_mul_f32 v[16:17], v[16:17], v[40:41] op_sel:[1,0] op_sel_hi:[0,1]
	v_sub_f32_e32 v13, v12, v13
	v_add_f32_e32 v12, v16, v17
	v_pk_mul_f32 v[16:17], v[4:5], v[14:15]
	s_nop 0
	v_pk_mul_f32 v[14:15], v[16:17], v[42:43]
	v_pk_mul_f32 v[16:17], v[16:17], v[42:43] op_sel:[1,0] op_sel_hi:[0,1]
	flat_load_dwordx4 v[32:35], v[52:53] offset:16
	flat_load_dwordx4 v[40:43], v[52:53] offset:80
	flat_load_dwordx4 v[44:47], v[56:57] offset:32
	v_sub_f32_e32 v15, v14, v15
	v_add_f32_e32 v14, v16, v17
	v_mov_b32_e32 v16, v20
	v_mov_b32_e32 v17, v24
	v_mov_b32_e32 v24, v21
	s_waitcnt vmcnt(0) lgkmcnt(0)
	v_mov_b32_e32 v18, v32
	v_mov_b32_e32 v19, v40
	v_pk_mul_f32 v[16:17], v[16:17], v[18:19]
	v_mov_b32_e32 v40, v33
	v_pk_mul_f32 v[18:19], v[4:5], v[16:17]
	s_nop 0
	v_pk_mul_f32 v[16:17], v[18:19], v[44:45]
	v_pk_mul_f32 v[18:19], v[18:19], v[44:45] op_sel:[1,0] op_sel_hi:[0,1]
	v_sub_f32_e32 v17, v16, v17
	v_add_f32_e32 v16, v18, v19
	v_pk_mul_f32 v[18:19], v[24:25], v[40:41]
	v_mov_b32_e32 v24, v34
	v_pk_mul_f32 v[20:21], v[4:5], v[18:19]
	v_mov_b32_e32 v25, v42
	v_pk_mul_f32 v[18:19], v[20:21], v[46:47]
	v_pk_mul_f32 v[20:21], v[20:21], v[46:47] op_sel:[1,0] op_sel_hi:[0,1]
	flat_load_dwordx4 v[44:47], v[56:57] offset:48
	v_sub_f32_e32 v19, v18, v19
	v_add_f32_e32 v18, v20, v21
	v_mov_b32_e32 v20, v22
	v_mov_b32_e32 v21, v26
	v_pk_mul_f32 v[20:21], v[20:21], v[24:25]
	v_mov_b32_e32 v26, v23
	v_pk_mul_f32 v[24:25], v[4:5], v[20:21]
	v_mov_b32_e32 v42, v35
	v_pk_mul_f32 v[22:23], v[26:27], v[42:43]
	ds_read_b128 v[32:35], v54 offset:96
	v_cvt_pk_bf16_f32 v10, v16, v18
	s_waitcnt vmcnt(0) lgkmcnt(0)
	v_pk_mul_f32 v[20:21], v[24:25], v[44:45]
	v_pk_mul_f32 v[24:25], v[24:25], v[44:45] op_sel:[1,0] op_sel_hi:[0,1]
	v_sub_f32_e32 v21, v20, v21
	v_add_f32_e32 v20, v24, v25
	v_pk_mul_f32 v[24:25], v[4:5], v[22:23]
	s_nop 0
	v_pk_mul_f32 v[22:23], v[24:25], v[46:47]
	v_pk_mul_f32 v[24:25], v[24:25], v[46:47] op_sel:[1,0] op_sel_hi:[0,1]
	flat_load_dwordx4 v[40:43], v[52:53] offset:32
	flat_load_dwordx4 v[44:47], v[52:53] offset:96
	flat_load_dwordx4 v[48:51], v[56:57] offset:64
	v_sub_f32_e32 v23, v22, v23
	v_add_f32_e32 v22, v24, v25
	v_mov_b32_e32 v24, v28
	v_mov_b32_e32 v25, v32
	v_mov_b32_e32 v32, v29
	s_waitcnt vmcnt(0) lgkmcnt(0)
	v_mov_b32_e32 v26, v40
	v_mov_b32_e32 v27, v44
	v_pk_mul_f32 v[24:25], v[24:25], v[26:27]
	v_mov_b32_e32 v44, v41
	v_pk_mul_f32 v[26:27], v[4:5], v[24:25]
	s_nop 0
	v_pk_mul_f32 v[24:25], v[26:27], v[48:49]
	v_pk_mul_f32 v[26:27], v[26:27], v[48:49] op_sel:[1,0] op_sel_hi:[0,1]
	v_sub_f32_e32 v25, v24, v25
	v_add_f32_e32 v24, v26, v27
	v_pk_mul_f32 v[26:27], v[32:33], v[44:45]
	v_mov_b32_e32 v32, v42
	v_pk_mul_f32 v[28:29], v[4:5], v[26:27]
	v_mov_b32_e32 v33, v46
	v_pk_mul_f32 v[26:27], v[28:29], v[50:51]
	v_pk_mul_f32 v[28:29], v[28:29], v[50:51] op_sel:[1,0] op_sel_hi:[0,1]
	flat_load_dwordx4 v[48:51], v[56:57] offset:80
	v_sub_f32_e32 v27, v26, v27
	v_add_f32_e32 v26, v28, v29
	v_mov_b32_e32 v28, v30
	v_mov_b32_e32 v29, v34
	v_pk_mul_f32 v[28:29], v[28:29], v[32:33]
	v_mov_b32_e32 v34, v31
	v_pk_mul_f32 v[32:33], v[4:5], v[28:29]
	v_mov_b32_e32 v46, v43
	v_pk_mul_f32 v[30:31], v[34:35], v[46:47]
	ds_read_b128 v[40:43], v54 offset:112
	s_waitcnt vmcnt(0) lgkmcnt(0)
	v_pk_mul_f32 v[28:29], v[32:33], v[48:49]
	v_pk_mul_f32 v[32:33], v[32:33], v[48:49] op_sel:[1,0] op_sel_hi:[0,1]
	v_sub_f32_e32 v29, v28, v29
	v_add_f32_e32 v28, v32, v33
	v_pk_mul_f32 v[32:33], v[4:5], v[30:31]
	s_nop 0
	v_pk_mul_f32 v[30:31], v[32:33], v[50:51]
	v_pk_mul_f32 v[32:33], v[32:33], v[50:51] op_sel:[1,0] op_sel_hi:[0,1]
	flat_load_dwordx4 v[44:47], v[52:53] offset:48
	flat_load_dwordx4 v[48:51], v[52:53] offset:112
	v_sub_f32_e32 v31, v30, v31
	flat_load_dwordx4 v[52:55], v[56:57] offset:96
	v_add_f32_e32 v30, v32, v33
	v_mov_b32_e32 v32, v36
	v_mov_b32_e32 v33, v40
	v_mov_b32_e32 v40, v37
	s_waitcnt vmcnt(0) lgkmcnt(0)
	v_mov_b32_e32 v34, v44
	v_mov_b32_e32 v35, v48
	v_pk_mul_f32 v[32:33], v[32:33], v[34:35]
	v_mov_b32_e32 v48, v45
	v_pk_mul_f32 v[34:35], v[4:5], v[32:33]
	v_lshl_add_u64 v[44:45], s[6:7], 1, v[2:3]
	v_lshl_add_u32 v251, s6, 1, v1
	v_pk_mul_f32 v[32:33], v[34:35], v[52:53]
	v_pk_mul_f32 v[34:35], v[34:35], v[52:53] op_sel:[1,0] op_sel_hi:[0,1]
	v_sub_f32_e32 v33, v32, v33
	v_add_f32_e32 v32, v34, v35
	v_pk_mul_f32 v[34:35], v[40:41], v[48:49]
	v_mov_b32_e32 v40, v46
	v_pk_mul_f32 v[36:37], v[4:5], v[34:35]
	v_mov_b32_e32 v41, v50
	v_pk_mul_f32 v[34:35], v[36:37], v[54:55]
	v_pk_mul_f32 v[36:37], v[36:37], v[54:55] op_sel:[1,0] op_sel_hi:[0,1]
	flat_load_dwordx4 v[52:55], v[56:57] offset:112
	v_sub_f32_e32 v35, v34, v35
	v_add_f32_e32 v34, v36, v37
	v_mov_b32_e32 v36, v38
	v_mov_b32_e32 v37, v42
	v_pk_mul_f32 v[36:37], v[36:37], v[40:41]
	v_mov_b32_e32 v42, v39
	v_pk_mul_f32 v[40:41], v[4:5], v[36:37]
	v_mov_b32_e32 v50, v47
	v_pk_mul_f32 v[38:39], v[42:43], v[50:51]
	v_cvt_pk_bf16_f32 v42, v17, v19
	v_cvt_pk_bf16_f32 v43, v21, v23
	s_mov_b64 s[6:7], 32
	s_waitcnt vmcnt(0) lgkmcnt(0)
	v_pk_mul_f32 v[36:37], v[40:41], v[52:53]
	v_pk_mul_f32 v[40:41], v[40:41], v[52:53] op_sel:[1,0] op_sel_hi:[0,1]
	v_sub_f32_e32 v37, v36, v37
	v_add_f32_e32 v36, v40, v41
	v_pk_mul_f32 v[40:41], v[4:5], v[38:39]
	s_nop 0
	v_pk_mul_f32 v[38:39], v[40:41], v[54:55]
	v_pk_mul_f32 v[40:41], v[40:41], v[54:55] op_sel:[1,0] op_sel_hi:[0,1]
	v_sub_f32_e32 v39, v38, v39
	v_add_f32_e32 v38, v40, v41
	v_cvt_pk_bf16_f32 v40, v9, v11
	v_cvt_pk_bf16_f32 v41, v13, v15
	v_cvt_pk_bf16_f32 v9, v12, v14
	v_cvt_pk_bf16_f32 v11, v20, v22
	ds_write_b128 v251, v[40:43]
	ds_write_b128 v251, v[8:11] offset:32
	s_nop 0
	v_cvt_pk_bf16_f32 v40, v25, v27
	v_cvt_pk_bf16_f32 v41, v29, v31
	v_cvt_pk_bf16_f32 v42, v33, v35
	v_cvt_pk_bf16_f32 v43, v37, v39
	ds_write_b128 v251, v[40:43] offset:16
	v_cvt_pk_bf16_f32 v8, v24, v26
	v_cvt_pk_bf16_f32 v9, v28, v30
	v_cvt_pk_bf16_f32 v10, v32, v34
	v_cvt_pk_bf16_f32 v11, v36, v38
	ds_write_b128 v251, v[8:11] offset:48
	s_cbranch_vccz .LBB0_581
	v_and_b32_e32 v14, 63, v170
	v_lshrrev_b32_e32 v15, 3, v14
	v_sub_u32_e32 v15, v15, v14
	v_and_b32_e32 v14, 7, v14
	v_lshlrev_b32_e32 v14, 4, v14
	v_mul_i32_i24_e32 v8, 0x1400, v15
	v_add_u32_e32 v8, v8, v14
	v_mul_i32_i24_e32 v15, 0x110, v15
	v_add3_u32 v15, v15, v14, v1
	s_waitcnt lgkmcnt(0)
	ds_read_b128 v[4:7], v15 offset:0
	v_mov_b32_e32 v10, v8
	v_ashrrev_i32_e32 v11, 31, v10
	v_lshl_add_u64 v[12:13], v[10:11], 0, v[2:3]
	s_waitcnt lgkmcnt(0)
	global_store_dwordx4 v[12:13], v[4:7], off
	s_nop 1
	ds_read_b128 v[4:7], v15 offset:2176
	v_add_u32_e32 v10, 0xa000, v8
	v_ashrrev_i32_e32 v11, 31, v10
	v_lshl_add_u64 v[12:13], v[10:11], 0, v[2:3]
	s_waitcnt lgkmcnt(0)
	global_store_dwordx4 v[12:13], v[4:7], off
	s_nop 1
	ds_read_b128 v[4:7], v15 offset:4352
	v_add_u32_e32 v10, 0x14000, v8
	v_ashrrev_i32_e32 v11, 31, v10
	v_lshl_add_u64 v[12:13], v[10:11], 0, v[2:3]
	s_waitcnt lgkmcnt(0)
	global_store_dwordx4 v[12:13], v[4:7], off
	s_nop 1
	ds_read_b128 v[4:7], v15 offset:6528
	v_add_u32_e32 v10, 0x1e000, v8
	v_ashrrev_i32_e32 v11, 31, v10
	v_lshl_add_u64 v[12:13], v[10:11], 0, v[2:3]
	s_waitcnt lgkmcnt(0)
	global_store_dwordx4 v[12:13], v[4:7], off
	s_nop 1
	ds_read_b128 v[4:7], v15 offset:8704
	v_add_u32_e32 v10, 0x28000, v8
	v_ashrrev_i32_e32 v11, 31, v10
	v_lshl_add_u64 v[12:13], v[10:11], 0, v[2:3]
	s_waitcnt lgkmcnt(0)
	global_store_dwordx4 v[12:13], v[4:7], off
	s_nop 1
	ds_read_b128 v[4:7], v15 offset:10880
	v_add_u32_e32 v10, 0x32000, v8
	v_ashrrev_i32_e32 v11, 31, v10
	v_lshl_add_u64 v[12:13], v[10:11], 0, v[2:3]
	s_waitcnt lgkmcnt(0)
	global_store_dwordx4 v[12:13], v[4:7], off
	s_nop 1
	ds_read_b128 v[4:7], v15 offset:13056
	v_add_u32_e32 v10, 0x3c000, v8
	v_ashrrev_i32_e32 v11, 31, v10
	v_lshl_add_u64 v[12:13], v[10:11], 0, v[2:3]
	s_waitcnt lgkmcnt(0)
	global_store_dwordx4 v[12:13], v[4:7], off
	s_nop 1
	ds_read_b128 v[4:7], v15 offset:15232
	v_add_u32_e32 v10, 0x46000, v8
	v_ashrrev_i32_e32 v11, 31, v10
	v_lshl_add_u64 v[12:13], v[10:11], 0, v[2:3]
	s_waitcnt lgkmcnt(0)
	global_store_dwordx4 v[12:13], v[4:7], off
	s_nop 1
	s_branch .LBB0_537
